# on top of v7: HGRN2 output phase (r3) chunk loop: LDS fragment reads for the inter-chunk and state-update MFMA sections issued several ahead with counted lgkmcnt instead of read-wait-MFMA singles
# speedup vs baseline: 1.0057x; 1.0038x over previous
; #define LAS __attribute__((address_space(3)))
; __device__ __forceinline__ unsigned pkbf(float lo, float hi) { const f32x2_t v = {lo, hi}; const bf16x2_t b = __builtin_convertvector(v, bf16x2_t); return __builtin_bit_cast(unsigned, b); }
; #define MFMA16(a, b, c) __builtin_amdgcn_mfma_f32_16x16x32_bf16((a), (b), (c), 0, 0, 0)
; __device__ __forceinline__ void hgrn_r3(const GAS bf16* proj, const GAS float* RU, const GAS float* RD, GAS bf16* y, int TOKG, const GAS float* ogain, unsigned char* lds, int tid, int lane, int wave, int bid, int G) {
;     ...
;                   v2u w; w.x = pkbf(s0 <= t ? a[0] : 0.f, s0 + 1 <= t ? a[1] : 0.f); w.y = pkbf(s0 + 2 <= t ? a[2] : 0.f, s0 + 3 <= t ? a[3] : 0.f);
;                   *(LAS v2u*)(L + H3_AM + t * HS + s0 * 2) = w; } }
;             f32x4h acc[4];
; #pragma unroll
;             for (int t2 = 0; t2 < 4; ++t2) acc[t2] = (f32x4h){0.f, 0.f, 0.f, 0.f};
; #pragma unroll
;             for (int t2 = 0; t2 < 4; ++t2)
; #pragma unroll
;                 for (int ks = 0; ks < 4; ++ks) { const bf16x8 qf = *(const LAS bf16x8*)(L + H3_QH + (16 * t2 + fr) * HQS + (32 * ks + 8 * fq) * 2); acc[t2] = MFMA16(sf[ks], qf, acc[t2]); }
;             bf16x8 vf[2];
; #pragma unroll
;             for (int ks = 0; ks < 2; ++ks) vf[ks] = *(const LAS bf16x8*)(L + H3_VT + (16 * wave + fr) * HS + (32 * ks + 8 * fq) * 2);
; #pragma unroll
;             for (int nk = 0; nk < 8; ++nk) { const f32x4h dk = *(const LAS f32x4h*)(decl + 16 * nk + 4 * fq); Sm[nk] = Sm[nk] * dk;
; #pragma unroll
;                 for (int ks = 0; ks < 2; ++ks) { const bf16x8 kf = *(const LAS bf16x8*)(L + H3_KT + (16 * nk + fr) * HS + (32 * ks + 8 * fq) * 2); Sm[nk] = MFMA16(kf, vf[ks], Sm[nk]); } }
;             __syncthreads();
; #pragma unroll
;             for (int t2 = 0; t2 < 4; ++t2)
; #pragma unroll
;                 for (int ks = 0; ks < 2; ++ks) { const bf16x8 af = *(const LAS bf16x8*)(L + H3_AM + (16 * t2 + fr) * HS + (32 * ks + 8 * fq) * 2); acc[t2] = MFMA16(vf[ks], af, acc[t2]); }
; #pragma unroll
;             for (int t2 = 0; t2 < 4; ++t2) { float ss = acc[t2][0] * acc[t2][0] + acc[t2][1] * acc[t2][1] + acc[t2][2] * acc[t2][2] + acc[t2][3] * acc[t2][3];
;                 ss += __shfl_xor(ss, 16); ss += __shfl_xor(ss, 32); if (fq == 0) red[(16 * t2 + fr) * 8 + wave] = ss; }
.LBB0_392:
	s_nop 7
	v_cndmask_b32_e64 v52, v52, 0, s[30:31]
	v_cndmask_b32_e64 v53, 0, v53, s[34:35]
	v_cvt_pk_bf16_f32 v52, v52, v53
	v_cndmask_b32_e64 v53, v54, 0, s[36:37]
	v_cndmask_b32_e64 v54, v55, 0, s[38:39]
	v_cvt_pk_bf16_f32 v53, v53, v54
	ds_write_b64 v128, v[52:53]
	ds_read_b128 v[214:217], v129
	ds_read_b128 v[218:221], v129 offset:64
	ds_read_b128 v[222:225], v129 offset:128
	ds_read_b128 v[226:229], v129 offset:192
	ds_read_b128 v[230:233], v129 offset:4352
	ds_read_b128 v[64:67], v129 offset:4416
	s_waitcnt lgkmcnt(5)
	v_mfma_f32_16x16x32_bf16 v[52:55], v[48:51], v[214:217], 0
	ds_read_b128 v[214:217], v129 offset:4480
	s_waitcnt lgkmcnt(5)
	v_mfma_f32_16x16x32_bf16 v[52:55], v[44:47], v[218:221], v[52:55]
	ds_read_b128 v[218:221], v129 offset:4544
	s_waitcnt lgkmcnt(5)
	v_mfma_f32_16x16x32_bf16 v[52:55], v[40:43], v[222:225], v[52:55]
	ds_read_b128 v[222:225], v129 offset:8704
	s_waitcnt lgkmcnt(5)
	v_mfma_f32_16x16x32_bf16 v[52:55], v[36:39], v[226:229], v[52:55]
	ds_read_b128 v[226:229], v129 offset:8768
	s_waitcnt lgkmcnt(5)
	v_mfma_f32_16x16x32_bf16 v[56:59], v[48:51], v[230:233], 0
	ds_read_b128 v[230:233], v129 offset:8832
	s_waitcnt lgkmcnt(5)
	v_mfma_f32_16x16x32_bf16 v[56:59], v[44:47], v[64:67], v[56:59]
	ds_read_b128 v[64:67], v129 offset:8896
	s_waitcnt lgkmcnt(5)
	v_mfma_f32_16x16x32_bf16 v[56:59], v[40:43], v[214:217], v[56:59]
	ds_read_b128 v[214:217], v129 offset:13056
	s_waitcnt lgkmcnt(5)
	v_mfma_f32_16x16x32_bf16 v[56:59], v[36:39], v[218:221], v[56:59]
	ds_read_b128 v[218:221], v129 offset:13120
	s_waitcnt lgkmcnt(5)
	v_mfma_f32_16x16x32_bf16 v[60:63], v[48:51], v[222:225], 0
	ds_read_b128 v[222:225], v129 offset:13184
	s_waitcnt lgkmcnt(5)
	v_mfma_f32_16x16x32_bf16 v[60:63], v[44:47], v[226:229], v[60:63]
	ds_read_b128 v[226:229], v129 offset:13248
	s_waitcnt lgkmcnt(5)
	v_mfma_f32_16x16x32_bf16 v[60:63], v[40:43], v[230:233], v[60:63]
	s_waitcnt lgkmcnt(4)
	v_mfma_f32_16x16x32_bf16 v[60:63], v[36:39], v[64:67], v[60:63]
	s_waitcnt lgkmcnt(3)
	v_mfma_f32_16x16x32_bf16 v[48:51], v[48:51], v[214:217], 0
	s_waitcnt lgkmcnt(2)
	v_mfma_f32_16x16x32_bf16 v[44:47], v[44:47], v[218:221], v[48:51]
	s_waitcnt lgkmcnt(1)
	v_mfma_f32_16x16x32_bf16 v[40:43], v[40:43], v[222:225], v[44:47]
	s_waitcnt lgkmcnt(0)
	v_mfma_f32_16x16x32_bf16 v[40:43], v[36:39], v[226:229], v[40:43]
	s_nop 3
	ds_read_b128 v[44:47], v130 offset:52224
	ds_read_b128 v[36:39], v130 offset:52288
	ds_read_b128 v[48:51], v117
	ds_read_b128 v[214:217], v131
	ds_read_b128 v[218:221], v131 offset:64
	ds_read_b128 v[222:225], v117 offset:64
	ds_read_b128 v[226:229], v131 offset:2304
	ds_read_b128 v[230:233], v131 offset:2368
	s_waitcnt lgkmcnt(4)
	v_pk_mul_f32 v[22:23], v[22:23], v[50:51]
	v_pk_mul_f32 v[20:21], v[20:21], v[48:49]
	s_nop 1
	v_mfma_f32_16x16x32_bf16 v[20:23], v[214:217], v[44:47], v[20:23]
	s_waitcnt lgkmcnt(3)
	v_mfma_f32_16x16x32_bf16 v[20:23], v[218:221], v[36:39], v[20:23]
	ds_read_b128 v[48:51], v117 offset:128
	ds_read_b128 v[214:217], v131 offset:4608
	ds_read_b128 v[218:221], v131 offset:4672
	s_waitcnt lgkmcnt(4)
	v_pk_mul_f32 v[6:7], v[6:7], v[224:225]
	v_pk_mul_f32 v[4:5], v[4:5], v[222:223]
	s_nop 1
	v_mfma_f32_16x16x32_bf16 v[4:7], v[226:229], v[44:47], v[4:7]
	s_waitcnt lgkmcnt(3)
	v_mfma_f32_16x16x32_bf16 v[4:7], v[230:233], v[36:39], v[4:7]
	ds_read_b128 v[222:225], v117 offset:192
	ds_read_b128 v[226:229], v131 offset:6912
	ds_read_b128 v[230:233], v131 offset:6976
	s_waitcnt lgkmcnt(4)
	v_pk_mul_f32 v[18:19], v[18:19], v[50:51]
	v_pk_mul_f32 v[16:17], v[16:17], v[48:49]
	s_nop 1
	v_mfma_f32_16x16x32_bf16 v[16:19], v[214:217], v[44:47], v[16:19]
	s_waitcnt lgkmcnt(3)
	v_mfma_f32_16x16x32_bf16 v[16:19], v[218:221], v[36:39], v[16:19]
	ds_read_b128 v[48:51], v117 offset:256
	ds_read_b128 v[214:217], v131 offset:9216
	ds_read_b128 v[218:221], v131 offset:9280
	s_waitcnt lgkmcnt(4)
	v_pk_mul_f32 v[10:11], v[10:11], v[224:225]
	v_pk_mul_f32 v[8:9], v[8:9], v[222:223]
	s_nop 1
	v_mfma_f32_16x16x32_bf16 v[8:11], v[226:229], v[44:47], v[8:11]
	s_waitcnt lgkmcnt(3)
	v_mfma_f32_16x16x32_bf16 v[8:11], v[230:233], v[36:39], v[8:11]
	ds_read_b128 v[222:225], v117 offset:320
	ds_read_b128 v[226:229], v131 offset:11520
	ds_read_b128 v[230:233], v131 offset:11584
	s_waitcnt lgkmcnt(4)
	v_pk_mul_f32 v[26:27], v[26:27], v[50:51]
	v_pk_mul_f32 v[24:25], v[24:25], v[48:49]
	s_nop 1
	v_mfma_f32_16x16x32_bf16 v[24:27], v[214:217], v[44:47], v[24:27]
	s_waitcnt lgkmcnt(3)
	v_mfma_f32_16x16x32_bf16 v[24:27], v[218:221], v[36:39], v[24:27]
	ds_read_b128 v[48:51], v117 offset:384
	ds_read_b128 v[214:217], v131 offset:13824
	ds_read_b128 v[218:221], v131 offset:13888
	s_waitcnt lgkmcnt(4)
	v_pk_mul_f32 v[14:15], v[14:15], v[224:225]
	v_pk_mul_f32 v[12:13], v[12:13], v[222:223]
	s_nop 1
	v_mfma_f32_16x16x32_bf16 v[12:15], v[226:229], v[44:47], v[12:15]
	s_waitcnt lgkmcnt(3)
	v_mfma_f32_16x16x32_bf16 v[12:15], v[230:233], v[36:39], v[12:15]
	ds_read_b128 v[222:225], v117 offset:448
	ds_read_b128 v[226:229], v131 offset:16128
	ds_read_b128 v[230:233], v131 offset:16192
	s_waitcnt lgkmcnt(4)
	v_pk_mul_f32 v[30:31], v[30:31], v[50:51]
	v_pk_mul_f32 v[28:29], v[28:29], v[48:49]
	s_nop 1
	v_mfma_f32_16x16x32_bf16 v[28:31], v[214:217], v[44:47], v[28:31]
	s_waitcnt lgkmcnt(3)
	v_mfma_f32_16x16x32_bf16 v[28:31], v[218:221], v[36:39], v[28:31]
	s_waitcnt lgkmcnt(1)
	v_pk_mul_f32 v[34:35], v[34:35], v[224:225]
	v_pk_mul_f32 v[32:33], v[32:33], v[222:223]
	s_nop 1
	v_mfma_f32_16x16x32_bf16 v[32:35], v[226:229], v[44:47], v[32:35]
	s_waitcnt lgkmcnt(0)
	s_barrier
	v_mfma_f32_16x16x32_bf16 v[32:35], v[230:233], v[36:39], v[32:35]
	ds_read_b128 v[48:51], v132
	s_waitcnt lgkmcnt(0)
	v_mfma_f32_16x16x32_bf16 v[48:51], v[44:47], v[48:51], v[52:55]
	s_nop 2
	ds_read_b128 v[52:55], v132 offset:64
	s_waitcnt lgkmcnt(0)
	v_mfma_f32_16x16x32_bf16 v[64:67], v[36:39], v[52:55], v[48:51]
	ds_read_b128 v[52:55], v132 offset:2368
	s_nop 1
	ds_read_b128 v[48:51], v132 offset:2304
	s_waitcnt lgkmcnt(0)
	v_mfma_f32_16x16x32_bf16 v[48:51], v[44:47], v[48:51], v[56:59]
	s_nop 2
	ds_read_b128 v[56:59], v132 offset:4672
	v_mfma_f32_16x16x32_bf16 v[52:55], v[36:39], v[52:55], v[48:51]
	s_nop 2
	ds_read_b128 v[48:51], v132 offset:4608
	s_waitcnt lgkmcnt(0)
	v_mfma_f32_16x16x32_bf16 v[48:51], v[44:47], v[48:51], v[60:63]
	v_mfma_f32_16x16x32_bf16 v[48:51], v[36:39], v[56:59], v[48:51]
	ds_read_b128 v[56:59], v132 offset:6912
	s_waitcnt lgkmcnt(0)
	v_mfma_f32_16x16x32_bf16 v[40:43], v[44:47], v[56:59], v[40:43]
	ds_read_b128 v[44:47], v132 offset:6976
	s_waitcnt lgkmcnt(0)
	v_mfma_f32_16x16x32_bf16 v[36:39], v[36:39], v[44:47], v[40:43]
	s_nop 4
	v_mul_f32_e32 v40, v65, v65
	v_fmac_f32_e32 v40, v64, v64
	v_fmac_f32_e32 v40, v66, v66
	v_fmac_f32_e32 v40, v67, v67
	ds_bpermute_b32 v41, v118, v40
	s_waitcnt lgkmcnt(0)
	v_add_f32_e32 v40, v40, v41
	ds_bpermute_b32 v41, v119, v40
	s_and_saveexec_b64 vcc, s[4:5]
	s_cbranch_execz .LBB0_394
	s_waitcnt lgkmcnt(0)
	v_add_f32_e32 v40, v40, v41
	ds_write_b32 v135, v40
